# slc tile loop: first six K-fragment LDS reads issued right after the barrier, before the scalar next-tile block
# baseline (speedup 1.0000x reference)
; #define LAS __attribute__((address_space(3)))
; DI int crow(int reg, int hi) { return (reg & 3) + 8 * (reg >> 2) + 4 * hi; }
; #define MFMA32(a, b, c) __builtin_amdgcn_mfma_f32_32x32x16_bf16((a), (b), (c), 0, 0, 0)
; template <bool CMP> DI void tile_compute(LAS unsigned char* lds, int buf, const bf16x8 (&q)[4], int lo, int hv, ASt& st, f32x16& imp0, f32x16& imp1, int jt, LAS float* wsf, int lane) {
;     ...
;     f32x16 p0 = {}, p1 = {};
; #pragma unroll
;     for (int s = 0; s < 4; ++s) { const LAS unsigned char* kb = kb0 + ((r ^ (4 * s + 2 * hi)) * 16);
;         const bf16x8 a0 = *(const LAS bf16x8*)(kb + s * 2048), a1 = *(const LAS bf16x8*)(kb + s * 2048 + 512);
;         p0 = MFMA32(a0, q[s], p0); p1 = MFMA32(a1, q[s], p1); }
;     const bool dead = lo > hv;
;     const bool part = !dead && (lo > 0 || hv < 63);
;     const bool anyPart = __builtin_amdgcn_ballot_w64(part) != 0ull;
;     if (anyPart) {
; #pragma unroll
;         for (int rg = 0; rg < 16; ++rg) { const int k0 = crow(rg, hi), k1 = k0 + 32;
;             p0[rg] = (k0 >= lo && k0 <= hv) ? p0[rg] : NEGB; p1[rg] = (k1 >= lo && k1 <= hv) ? p1[rg] : NEGB; }
;     }
; DI void nsa_unit(const Ctx& c0, int b, int g, int i, LAS unsigned char* lds) {
;     ...
;         for (;;) {
;             tile_stage(tr, lds, k & 1, tid);
;             __syncthreads();
;             const bool more = rem != 0ull; int nn = 0;
;             if (more) { nn = __builtin_ctzll(rem); rem &= rem - 1ull; tr = tile_fetch(Kg, Vg, 64 * nn, tid); }
;             const bool selb = (mysel >> n) & 1ull;
;             const int lo = selb ? 0 : 64; const int hv = (n == i) ? ql : 63;
.LBB0_568:
	s_and_b32 s14, s3, 0x2000
	s_add_i32 s84, s14, 0
	s_cmp_eq_u64 s[98:99], 0
	s_cselect_b64 s[78:79], -1, 0
	s_cselect_b64 vcc, 0, -1
	s_waitcnt vmcnt(0) lgkmcnt(0)
	s_barrier
	v_lshrrev_b64 v[4:5], s100, v[116:117]
	v_add_u32_e32 v5, s84, v137
	v_add_u32_e32 v6, v5, v139
	ds_read_b128 v[66:69], v6
	ds_read_b128 v[50:53], v6 offset:512
	v_add_u32_e32 v6, v5, v143
	ds_read_b128 v[12:15], v6 offset:2048
	ds_read_b128 v[108:111], v6 offset:2560
	v_add_u32_e32 v6, v5, v146
	v_add_u32_e32 v5, v5, v147
	ds_read_b128 v[112:115], v6 offset:4096
	ds_read_b128 v[120:123], v6 offset:4608
	s_and_saveexec_b64 s[14:15], vcc
	s_cbranch_execz .LBB0_570
	s_ff1_i32_b64 s101, s[98:99]
	s_add_u32 s80, s98, -1
	s_addc_u32 s81, s99, -1
	s_and_b64 s[98:99], s[98:99], s[80:81]
	s_lshl_b32 s82, s101, 13
	s_add_u32 s80, s88, s82
	s_addc_u32 s81, s89, 0
	s_add_u32 s82, s90, s82
	s_addc_u32 s83, s91, 0
	s_sub_i32 m0, m0, 0x4000
	s_xor_b32 m0, m0, 0x2000
	s_nop 0
	global_load_lds_dwordx4 v246, s[80:81]
	s_add_i32 m0, m0, 0x4000
	s_nop 0
	global_load_lds_dwordx4 v247, s[82:83]
.LBB0_570:
	s_or_b64 exec, exec, s[14:15]
	s_cmp_eq_u32 s25, s100
	s_cselect_b64 s[80:81], -1, 0
	v_and_b32_e32 v2, 1, v4
	v_cmp_eq_u64_e32 vcc, 0, v[2:3]
	v_cndmask_b32_e64 v4, 63, v125, s[80:81]
	v_cmp_ne_u32_e64 s[82:83], 63, v4
	v_cndmask_b32_e64 v2, 0, 64, vcc
	s_waitcnt lgkmcnt(5)
	v_mfma_f32_32x32x16_bf16 v[66:81], v[66:69], v[82:85], 0
	v_cmp_gt_u32_e64 s[80:81], v2, v4
	s_or_b64 s[14:15], s[82:83], vcc
	s_xor_b64 vcc, s[14:15], s[80:81]
	s_waitcnt lgkmcnt(4)
	v_mfma_f32_32x32x16_bf16 v[50:65], v[50:53], v[82:85], 0
	s_waitcnt lgkmcnt(3)
	v_mfma_f32_32x32x16_bf16 v[66:81], v[12:15], v[90:93], v[66:81]
	ds_read_b128 v[12:15], v5 offset:6144
	s_waitcnt lgkmcnt(3)
	v_mfma_f32_32x32x16_bf16 v[50:65], v[108:111], v[90:93], v[50:65]
	ds_read_b128 v[108:111], v5 offset:6656
	v_cndmask_b32_e64 v5, 0, 1, vcc
	v_cmp_ne_u32_e64 s[82:83], 0, v5
	s_cmp_eq_u64 s[82:83], 0
	s_cselect_b64 s[14:15], -1, 0
	s_waitcnt lgkmcnt(3)
	v_mfma_f32_32x32x16_bf16 v[66:81], v[112:115], v[86:89], v[66:81]
	s_waitcnt lgkmcnt(2)
	v_mfma_f32_32x32x16_bf16 v[50:65], v[120:123], v[86:89], v[50:65]
	s_waitcnt lgkmcnt(1)
	v_mfma_f32_32x32x16_bf16 v[66:81], v[12:15], v[94:97], v[66:81]
	s_waitcnt lgkmcnt(0)
	v_mfma_f32_32x32x16_bf16 v[50:65], v[108:111], v[94:97], v[50:65]
	s_cbranch_vccz .LBB0_572
	v_cmp_lt_u32_e32 vcc, v148, v2
	v_cmp_gt_u32_e64 s[82:83], v148, v4
	s_or_b64 vcc, s[82:83], vcc
	s_nop 6
	v_cndmask_b32_e32 v66, v66, v222, vcc
	v_cmp_lt_u32_e32 vcc, v149, v2
	v_cmp_gt_u32_e64 s[82:83], v149, v4
	s_or_b64 vcc, s[82:83], vcc
	v_cndmask_b32_e32 v50, v50, v222, vcc
	v_cmp_lt_u32_e32 vcc, v154, v2
	v_cmp_ge_u32_e64 s[82:83], v148, v4
	s_or_b64 vcc, s[82:83], vcc
	v_cndmask_b32_e32 v67, v67, v222, vcc
	v_cmp_lt_u32_e32 vcc, v155, v2
	v_cmp_gt_u32_e64 s[82:83], v155, v4
	s_or_b64 vcc, s[82:83], vcc
	v_cndmask_b32_e32 v51, v51, v222, vcc
	v_cmp_lt_u32_e32 vcc, v156, v2
	v_cmp_gt_u32_e64 s[82:83], v156, v4
	s_or_b64 vcc, s[82:83], vcc
	v_cndmask_b32_e32 v68, v68, v222, vcc
	v_cmp_lt_u32_e32 vcc, v157, v2
	v_cmp_gt_u32_e64 s[82:83], v157, v4
	s_or_b64 vcc, s[82:83], vcc
	v_cndmask_b32_e32 v52, v52, v222, vcc
	v_cmp_lt_u32_e32 vcc, v158, v2
	v_cmp_gt_u32_e64 s[82:83], v158, v4
	s_or_b64 vcc, s[82:83], vcc
	v_cndmask_b32_e32 v69, v69, v222, vcc
	v_cmp_lt_u32_e32 vcc, v159, v2
	v_cmp_gt_u32_e64 s[82:83], v159, v4
	s_or_b64 vcc, s[82:83], vcc
	v_cndmask_b32_e32 v53, v53, v222, vcc
	v_cmp_lt_u32_e32 vcc, v160, v2
	v_cmp_gt_u32_e64 s[82:83], v160, v4
	s_or_b64 vcc, s[82:83], vcc
	v_cndmask_b32_e32 v70, v70, v222, vcc
	v_cmp_lt_u32_e32 vcc, v161, v2
	v_cmp_gt_u32_e64 s[82:83], v161, v4
	s_or_b64 vcc, s[82:83], vcc
	v_cndmask_b32_e32 v54, v54, v222, vcc
	v_cmp_lt_u32_e32 vcc, v162, v2
	v_cmp_gt_u32_e64 s[82:83], v162, v4
	s_or_b64 vcc, s[82:83], vcc
	v_cndmask_b32_e32 v71, v71, v222, vcc
	v_cmp_lt_u32_e32 vcc, v163, v2
	v_cmp_gt_u32_e64 s[82:83], v163, v4
	s_or_b64 vcc, s[82:83], vcc
	v_cndmask_b32_e32 v55, v55, v222, vcc
	v_cmp_lt_u32_e32 vcc, v164, v2
	v_cmp_gt_u32_e64 s[82:83], v164, v4
	s_or_b64 vcc, s[82:83], vcc
	v_cndmask_b32_e32 v72, v72, v222, vcc
	v_cmp_lt_u32_e32 vcc, v165, v2
	v_cmp_gt_u32_e64 s[82:83], v165, v4
	s_or_b64 vcc, s[82:83], vcc
	v_cndmask_b32_e32 v56, v56, v222, vcc
	v_cmp_lt_u32_e32 vcc, v166, v2
	v_cmp_gt_u32_e64 s[82:83], v166, v4
	s_or_b64 vcc, s[82:83], vcc
	v_cndmask_b32_e32 v73, v73, v222, vcc
	v_cmp_lt_u32_e32 vcc, v167, v2
	v_cmp_gt_u32_e64 s[82:83], v167, v4
	s_or_b64 vcc, s[82:83], vcc
	v_cndmask_b32_e32 v57, v57, v222, vcc
	v_cmp_lt_u32_e32 vcc, v168, v2
	v_cmp_gt_u32_e64 s[82:83], v168, v4
	s_or_b64 vcc, s[82:83], vcc
	v_cndmask_b32_e32 v74, v74, v222, vcc
	v_cmp_lt_u32_e32 vcc, v169, v2
	v_cmp_gt_u32_e64 s[82:83], v169, v4
	s_or_b64 vcc, s[82:83], vcc
	v_cndmask_b32_e32 v58, v58, v222, vcc
	v_cmp_lt_u32_e32 vcc, v170, v2
	v_cmp_gt_u32_e64 s[82:83], v170, v4
	s_or_b64 vcc, s[82:83], vcc
	v_cndmask_b32_e32 v75, v75, v222, vcc
	v_cmp_lt_u32_e32 vcc, v171, v2
	v_cmp_gt_u32_e64 s[82:83], v171, v4
	s_or_b64 vcc, s[82:83], vcc
	v_cndmask_b32_e32 v59, v59, v222, vcc
	v_cmp_lt_u32_e32 vcc, v172, v2
	v_cmp_gt_u32_e64 s[82:83], v172, v4
	s_or_b64 vcc, s[82:83], vcc
	v_cndmask_b32_e32 v76, v76, v222, vcc
	v_cmp_lt_u32_e32 vcc, v173, v2
	v_cmp_gt_u32_e64 s[82:83], v173, v4
	s_or_b64 vcc, s[82:83], vcc
	v_cndmask_b32_e32 v60, v60, v222, vcc
	v_cmp_lt_u32_e32 vcc, v174, v2
	v_cmp_gt_u32_e64 s[82:83], v174, v4
	s_or_b64 vcc, s[82:83], vcc
	v_cndmask_b32_e32 v77, v77, v222, vcc
	v_cmp_lt_u32_e32 vcc, v175, v2
	v_cmp_gt_u32_e64 s[82:83], v175, v4
	s_or_b64 vcc, s[82:83], vcc
	v_cndmask_b32_e32 v61, v61, v222, vcc
	v_cmp_lt_u32_e32 vcc, v176, v2
	v_cmp_gt_u32_e64 s[82:83], v176, v4
	s_or_b64 vcc, s[82:83], vcc
	v_cndmask_b32_e32 v78, v78, v222, vcc
	v_cmp_lt_u32_e32 vcc, v177, v2
	v_cmp_gt_u32_e64 s[82:83], v177, v4
	s_or_b64 vcc, s[82:83], vcc
	v_cndmask_b32_e32 v62, v62, v222, vcc
	v_cmp_lt_u32_e32 vcc, v178, v2
	v_cmp_gt_u32_e64 s[82:83], v178, v4
	s_or_b64 vcc, s[82:83], vcc
	v_cndmask_b32_e32 v79, v79, v222, vcc
	v_cmp_lt_u32_e32 vcc, v179, v2
	v_cmp_gt_u32_e64 s[82:83], v179, v4
	s_or_b64 vcc, s[82:83], vcc
	v_cndmask_b32_e32 v63, v63, v222, vcc
	v_cmp_lt_u32_e32 vcc, v180, v2
	v_cmp_gt_u32_e64 s[82:83], v180, v4
	s_or_b64 vcc, s[82:83], vcc
	v_cndmask_b32_e32 v80, v80, v222, vcc
	v_cmp_lt_u32_e32 vcc, v181, v2
	v_cmp_gt_u32_e64 s[82:83], v181, v4
	s_or_b64 vcc, s[82:83], vcc
	v_cndmask_b32_e32 v64, v64, v222, vcc
	v_cmp_lt_u32_e32 vcc, v182, v2
	v_cmp_gt_u32_e64 s[82:83], v182, v4
	s_or_b64 vcc, s[82:83], vcc
	v_cndmask_b32_e32 v81, v81, v222, vcc
	v_cmp_lt_u32_e32 vcc, v183, v2
	v_cmp_gt_u32_e64 s[82:83], v183, v4
	s_or_b64 vcc, s[82:83], vcc
	v_cndmask_b32_e32 v65, v65, v222, vcc

; #define LAS __attribute__((address_space(3)))
; DI int crow(int reg, int hi) { return (reg & 3) + 8 * (reg >> 2) + 4 * hi; }
; #define MFMA32(a, b, c) __builtin_amdgcn_mfma_f32_32x32x16_bf16((a), (b), (c), 0, 0, 0)
; template <bool CMP> DI void tile_compute(LAS unsigned char* lds, int buf, const bf16x8 (&q)[4], int lo, int hv, ASt& st, f32x16& imp0, f32x16& imp1, int jt, LAS float* wsf, int lane) {
;     ...
;     f32x16 p0 = {}, p1 = {};
; #pragma unroll
;     for (int s = 0; s < 4; ++s) { const LAS unsigned char* kb = kb0 + ((r ^ (4 * s + 2 * hi)) * 16);
;         const bf16x8 a0 = *(const LAS bf16x8*)(kb + s * 2048), a1 = *(const LAS bf16x8*)(kb + s * 2048 + 512);
;         p0 = MFMA32(a0, q[s], p0); p1 = MFMA32(a1, q[s], p1); }
;     const bool dead = lo > hv;
;     const bool part = !dead && (lo > 0 || hv < 63);
;     const bool anyPart = __builtin_amdgcn_ballot_w64(part) != 0ull;
;     if (anyPart) {
; #pragma unroll
;         for (int rg = 0; rg < 16; ++rg) { const int k0 = crow(rg, hi), k1 = k0 + 32;
;             p0[rg] = (k0 >= lo && k0 <= hv) ? p0[rg] : NEGB; p1[rg] = (k1 >= lo && k1 <= hv) ? p1[rg] : NEGB; }
;     }
; DI void nsa_unit(const Ctx& c0, int b, int g, int i, LAS unsigned char* lds) {
;     ...
;         for (;;) {
;             tile_stage(tr, lds, k & 1, tid);
;             __syncthreads();
;             const bool more = rem != 0ull; int nn = 0;
;             if (more) { nn = __builtin_ctzll(rem); rem &= rem - 1ull; tr = tile_fetch(Kg, Vg, 64 * nn, tid); }
;             const bool selb = (mysel >> n) & 1ull;
;             const int lo = selb ? 0 : 64; const int hv = (n == i) ? ql : 63;
.LBB0_1181:
	s_and_b32 s16, s6, 0x2000
	s_add_i32 s28, s16, 0
	s_cmp_eq_u64 s[98:99], 0
	s_cselect_b64 s[80:81], -1, 0
	s_cselect_b64 vcc, 0, -1
	s_waitcnt vmcnt(0) lgkmcnt(0)
	s_barrier
	v_lshrrev_b64 v[4:5], s100, v[116:117]
	v_add_u32_e32 v5, s28, v137
	v_add_u32_e32 v6, v5, v139
	ds_read_b128 v[66:69], v6
	ds_read_b128 v[50:53], v6 offset:512
	v_add_u32_e32 v6, v5, v143
	ds_read_b128 v[12:15], v6 offset:2048
	ds_read_b128 v[108:111], v6 offset:2560
	v_add_u32_e32 v6, v5, v146
	v_add_u32_e32 v5, v5, v147
	ds_read_b128 v[112:115], v6 offset:4096
	ds_read_b128 v[120:123], v6 offset:4608
	s_and_saveexec_b64 s[16:17], vcc
	s_cbranch_execz .LBB0_1183
	s_ff1_i32_b64 s101, s[98:99]
	s_add_u32 s82, s98, -1
	s_addc_u32 s83, s99, -1
	s_and_b64 s[98:99], s[98:99], s[82:83]
	s_lshl_b32 s86, s101, 13
	s_add_u32 s82, s88, s86
	s_addc_u32 s83, s89, 0
	s_add_u32 s86, s90, s86
	s_addc_u32 s87, s91, 0
	s_sub_i32 m0, m0, 0x4000
	s_xor_b32 m0, m0, 0x2000
	s_nop 0
	global_load_lds_dwordx4 v246, s[82:83]
	s_add_i32 m0, m0, 0x4000
	s_nop 0
	global_load_lds_dwordx4 v247, s[86:87]
.LBB0_1183:
	s_or_b64 exec, exec, s[16:17]
	s_cmp_eq_u32 s27, s100
	s_cselect_b64 s[82:83], -1, 0
	v_and_b32_e32 v2, 1, v4
	v_cmp_eq_u64_e32 vcc, 0, v[2:3]
	v_cndmask_b32_e64 v4, 63, v125, s[82:83]
	v_cmp_ne_u32_e64 s[86:87], 63, v4
	v_cndmask_b32_e64 v2, 0, 64, vcc
	s_waitcnt lgkmcnt(5)
	v_mfma_f32_32x32x16_bf16 v[66:81], v[66:69], v[82:85], 0
	v_cmp_gt_u32_e64 s[82:83], v2, v4
	s_or_b64 s[16:17], s[86:87], vcc
	s_xor_b64 vcc, s[16:17], s[82:83]
	s_waitcnt lgkmcnt(4)
	v_mfma_f32_32x32x16_bf16 v[50:65], v[50:53], v[82:85], 0
	s_waitcnt lgkmcnt(3)
	v_mfma_f32_32x32x16_bf16 v[66:81], v[12:15], v[90:93], v[66:81]
	ds_read_b128 v[12:15], v5 offset:6144
	s_waitcnt lgkmcnt(3)
	v_mfma_f32_32x32x16_bf16 v[50:65], v[108:111], v[90:93], v[50:65]
	ds_read_b128 v[108:111], v5 offset:6656
	v_cndmask_b32_e64 v5, 0, 1, vcc
	v_cmp_ne_u32_e64 s[86:87], 0, v5
	s_cmp_eq_u64 s[86:87], 0
	s_cselect_b64 s[16:17], -1, 0
	s_waitcnt lgkmcnt(3)
	v_mfma_f32_32x32x16_bf16 v[66:81], v[112:115], v[86:89], v[66:81]
	s_waitcnt lgkmcnt(2)
	v_mfma_f32_32x32x16_bf16 v[50:65], v[120:123], v[86:89], v[50:65]
	s_waitcnt lgkmcnt(1)
	v_mfma_f32_32x32x16_bf16 v[66:81], v[12:15], v[94:97], v[66:81]
	s_waitcnt lgkmcnt(0)
	v_mfma_f32_32x32x16_bf16 v[50:65], v[108:111], v[94:97], v[50:65]
	s_cbranch_vccz .LBB0_1185
	v_cmp_lt_u32_e32 vcc, v148, v2
	v_cmp_gt_u32_e64 s[86:87], v148, v4
	s_or_b64 vcc, s[86:87], vcc
	s_nop 6
	v_cndmask_b32_e32 v66, v66, v217, vcc
	v_cmp_lt_u32_e32 vcc, v149, v2
	v_cmp_gt_u32_e64 s[86:87], v149, v4
	s_or_b64 vcc, s[86:87], vcc
	v_cndmask_b32_e32 v50, v50, v217, vcc
	v_cmp_lt_u32_e32 vcc, v155, v2
	v_cmp_ge_u32_e64 s[86:87], v148, v4
	s_or_b64 vcc, s[86:87], vcc
	v_cndmask_b32_e32 v67, v67, v217, vcc
	v_cmp_lt_u32_e32 vcc, v156, v2
	v_cmp_gt_u32_e64 s[86:87], v156, v4
	s_or_b64 vcc, s[86:87], vcc
	v_cndmask_b32_e32 v51, v51, v217, vcc
	v_cmp_lt_u32_e32 vcc, v157, v2
	v_cmp_gt_u32_e64 s[86:87], v157, v4
	s_or_b64 vcc, s[86:87], vcc
	v_cndmask_b32_e32 v68, v68, v217, vcc
	v_cmp_lt_u32_e32 vcc, v158, v2
	v_cmp_gt_u32_e64 s[86:87], v158, v4
	s_or_b64 vcc, s[86:87], vcc
	v_cndmask_b32_e32 v52, v52, v217, vcc
	v_cmp_lt_u32_e32 vcc, v159, v2
	v_cmp_gt_u32_e64 s[86:87], v159, v4
	s_or_b64 vcc, s[86:87], vcc
	v_cndmask_b32_e32 v69, v69, v217, vcc
	v_cmp_lt_u32_e32 vcc, v160, v2
	v_cmp_gt_u32_e64 s[86:87], v160, v4
	s_or_b64 vcc, s[86:87], vcc
	v_cndmask_b32_e32 v53, v53, v217, vcc
	v_cmp_lt_u32_e32 vcc, v161, v2
	v_cmp_gt_u32_e64 s[86:87], v161, v4
	s_or_b64 vcc, s[86:87], vcc
	v_cndmask_b32_e32 v70, v70, v217, vcc
	v_cmp_lt_u32_e32 vcc, v162, v2
	v_cmp_gt_u32_e64 s[86:87], v162, v4
	s_or_b64 vcc, s[86:87], vcc
	v_cndmask_b32_e32 v54, v54, v217, vcc
	v_cmp_lt_u32_e32 vcc, v163, v2
	v_cmp_gt_u32_e64 s[86:87], v163, v4
	s_or_b64 vcc, s[86:87], vcc
	v_cndmask_b32_e32 v71, v71, v217, vcc
	v_cmp_lt_u32_e32 vcc, v164, v2
	v_cmp_gt_u32_e64 s[86:87], v164, v4
	s_or_b64 vcc, s[86:87], vcc
	v_cndmask_b32_e32 v55, v55, v217, vcc
	v_cmp_lt_u32_e32 vcc, v165, v2
	v_cmp_gt_u32_e64 s[86:87], v165, v4
	s_or_b64 vcc, s[86:87], vcc
	v_cndmask_b32_e32 v72, v72, v217, vcc
	v_cmp_lt_u32_e32 vcc, v166, v2
	v_cmp_gt_u32_e64 s[86:87], v166, v4
	s_or_b64 vcc, s[86:87], vcc
	v_cndmask_b32_e32 v56, v56, v217, vcc
	v_cmp_lt_u32_e32 vcc, v167, v2
	v_cmp_gt_u32_e64 s[86:87], v167, v4
	s_or_b64 vcc, s[86:87], vcc
	v_cndmask_b32_e32 v73, v73, v217, vcc
	v_cmp_lt_u32_e32 vcc, v168, v2
	v_cmp_gt_u32_e64 s[86:87], v168, v4
	s_or_b64 vcc, s[86:87], vcc
	v_cndmask_b32_e32 v57, v57, v217, vcc
	v_cmp_lt_u32_e32 vcc, v169, v2
	v_cmp_gt_u32_e64 s[86:87], v169, v4
	s_or_b64 vcc, s[86:87], vcc
	v_cndmask_b32_e32 v74, v74, v217, vcc
	v_cmp_lt_u32_e32 vcc, v170, v2
	v_cmp_gt_u32_e64 s[86:87], v170, v4
	s_or_b64 vcc, s[86:87], vcc
	v_cndmask_b32_e32 v58, v58, v217, vcc
	v_cmp_lt_u32_e32 vcc, v171, v2
	v_cmp_gt_u32_e64 s[86:87], v171, v4
	s_or_b64 vcc, s[86:87], vcc
	v_cndmask_b32_e32 v75, v75, v217, vcc
	v_cmp_lt_u32_e32 vcc, v172, v2
	v_cmp_gt_u32_e64 s[86:87], v172, v4
	s_or_b64 vcc, s[86:87], vcc
	v_cndmask_b32_e32 v59, v59, v217, vcc
	v_cmp_lt_u32_e32 vcc, v173, v2
	v_cmp_gt_u32_e64 s[86:87], v173, v4
	s_or_b64 vcc, s[86:87], vcc
	v_cndmask_b32_e32 v76, v76, v217, vcc
	v_cmp_lt_u32_e32 vcc, v174, v2
	v_cmp_gt_u32_e64 s[86:87], v174, v4
	s_or_b64 vcc, s[86:87], vcc
	v_cndmask_b32_e32 v60, v60, v217, vcc
	v_cmp_lt_u32_e32 vcc, v175, v2
	v_cmp_gt_u32_e64 s[86:87], v175, v4
	s_or_b64 vcc, s[86:87], vcc
	v_cndmask_b32_e32 v77, v77, v217, vcc
	v_cmp_lt_u32_e32 vcc, v176, v2
	v_cmp_gt_u32_e64 s[86:87], v176, v4
	s_or_b64 vcc, s[86:87], vcc
	v_cndmask_b32_e32 v61, v61, v217, vcc
	v_cmp_lt_u32_e32 vcc, v177, v2
	v_cmp_gt_u32_e64 s[86:87], v177, v4
	s_or_b64 vcc, s[86:87], vcc
	v_cndmask_b32_e32 v78, v78, v217, vcc
	v_cmp_lt_u32_e32 vcc, v178, v2
	v_cmp_gt_u32_e64 s[86:87], v178, v4
	s_or_b64 vcc, s[86:87], vcc
	v_cndmask_b32_e32 v62, v62, v217, vcc
	v_cmp_lt_u32_e32 vcc, v179, v2
	v_cmp_gt_u32_e64 s[86:87], v179, v4
	s_or_b64 vcc, s[86:87], vcc
	v_cndmask_b32_e32 v79, v79, v217, vcc
	v_cmp_lt_u32_e32 vcc, v180, v2
	v_cmp_gt_u32_e64 s[86:87], v180, v4
	s_or_b64 vcc, s[86:87], vcc
	v_cndmask_b32_e32 v63, v63, v217, vcc
	v_cmp_lt_u32_e32 vcc, v181, v2
	v_cmp_gt_u32_e64 s[86:87], v181, v4
	s_or_b64 vcc, s[86:87], vcc
	v_cndmask_b32_e32 v80, v80, v217, vcc
	v_cmp_lt_u32_e32 vcc, v182, v2
	v_cmp_gt_u32_e64 s[86:87], v182, v4
	s_or_b64 vcc, s[86:87], vcc
	v_cndmask_b32_e32 v64, v64, v217, vcc
	v_cmp_lt_u32_e32 vcc, v183, v2
	v_cmp_gt_u32_e64 s[86:87], v183, v4
	s_or_b64 vcc, s[86:87], vcc
	v_cndmask_b32_e32 v81, v81, v217, vcc
	v_cmp_lt_u32_e32 vcc, v195, v2
	v_cmp_gt_u32_e64 s[86:87], v195, v4
	s_or_b64 vcc, s[86:87], vcc
	v_cndmask_b32_e32 v65, v65, v217, vcc
